# layer-0 residual GEMM epilogues: loads together, stores issued per 16-row group right after its adds (spread) instead of one 16-store burst
# baseline (speedup 1.0000x reference)
.LBB0_749:
	v_lshl_add_u32 v66, s12, 7, v99
	v_ashrrev_i32_e32 v64, 31, v66
	v_cmp_gt_i32_e32 vcc, s93, v66
	v_readlane_b32 s52, v254, 39
	v_add_u32_e32 v68, 0xffffc000, v66
	v_cndmask_b32_e32 v67, 0, v64, vcc
	v_readlane_b32 s53, v254, 40
	v_readlane_b32 s54, v254, 41
	v_readlane_b32 s55, v254, 42
	v_cndmask_b32_e32 v68, v68, v66, vcc
	v_mov_b32_e32 v69, v67
	v_mov_b32_e32 v64, s55
	v_mov_b32_e32 v78, s53
	v_mov_b32_e32 v79, s54
	v_mov_b32_e32 v80, s52
	v_cndmask_b32_e32 v71, v64, v78, vcc
	v_cndmask_b32_e32 v70, v79, v80, vcc
	v_lshlrev_b64 v[68:69], 12, v[68:69]
	v_lshl_add_u64 v[68:69], v[70:71], 0, v[68:69]
	v_lshl_or_b32 v70, s10, 7, v98
	v_ashrrev_i32_e32 v71, 31, v70
	v_lshlrev_b64 v[72:73], 2, v[70:71]
	v_lshl_add_u64 v[74:75], v[68:69], 0, v[72:73]
	s_waitcnt vmcnt(0)
	s_barrier
	v_readlane_b32 s12, v254, 3
	v_lshlrev_b64 v[76:77], 12, v[66:67]
	v_readlane_b32 s26, v254, 17
	v_readlane_b32 s27, v254, 18
	s_add_i32 s3, s3, s91
	s_add_i32 s92, s92, s28
	v_lshl_add_u64 v[76:77], s[26:27], 0, v[76:77]
	v_lshl_add_u64 v[76:77], v[76:77], 0, v[72:73]
	s_cmpk_gt_i32 s3, 0x87
	v_readlane_b32 s56, v254, 43
	v_readlane_b32 s57, v254, 44
	v_readlane_b32 s58, v254, 45
	v_readlane_b32 s59, v254, 46
	v_readlane_b32 s60, v254, 47
	v_readlane_b32 s61, v254, 48
	v_readlane_b32 s62, v254, 49
	v_readlane_b32 s63, v254, 50
	v_readlane_b32 s64, v254, 51
	v_readlane_b32 s65, v254, 52
	v_readlane_b32 s66, v254, 53
	v_readlane_b32 s67, v254, 54
	v_readlane_b32 s13, v254, 4
	v_readlane_b32 s14, v254, 5
	v_readlane_b32 s15, v254, 6
	v_readlane_b32 s16, v254, 7
	v_readlane_b32 s17, v254, 8
	v_readlane_b32 s18, v254, 9
	v_readlane_b32 s19, v254, 10
	v_readlane_b32 s20, v254, 11
	v_readlane_b32 s21, v254, 12
	v_readlane_b32 s22, v254, 13
	v_readlane_b32 s23, v254, 14
	v_readlane_b32 s24, v254, 15
	v_readlane_b32 s25, v254, 16
	v_or_b32_e32 v184, 16, v66
	v_cmp_gt_i32_e32 vcc, s93, v184
	v_add_u32_e32 v170, 0xffffc010, v66
	v_mov_b32_e32 v171, 0
	v_cndmask_b32_e32 v170, v170, v184, vcc
	v_cndmask_b32_e32 v187, v64, v78, vcc
	v_cndmask_b32_e32 v186, v79, v80, vcc
	v_lshlrev_b64 v[170:171], 12, v[170:171]
	v_lshl_add_u64 v[170:171], v[186:187], 0, v[170:171]
	v_lshl_add_u64 v[170:171], v[170:171], 0, v[72:73]
	v_mov_b32_e32 v178, v184
	v_mov_b32_e32 v179, 0
	v_lshlrev_b64 v[178:179], 12, v[178:179]
	v_lshl_add_u64 v[178:179], s[26:27], 0, v[178:179]
	v_lshl_add_u64 v[178:179], v[178:179], 0, v[72:73]
	v_or_b32_e32 v184, 32, v66
	v_cmp_gt_i32_e32 vcc, s93, v184
	v_add_u32_e32 v172, 0xffffc020, v66
	v_mov_b32_e32 v173, 0
	v_cndmask_b32_e32 v172, v172, v184, vcc
	v_cndmask_b32_e32 v187, v64, v78, vcc
	v_cndmask_b32_e32 v186, v79, v80, vcc
	v_lshlrev_b64 v[172:173], 12, v[172:173]
	v_lshl_add_u64 v[172:173], v[186:187], 0, v[172:173]
	v_lshl_add_u64 v[172:173], v[172:173], 0, v[72:73]
	v_mov_b32_e32 v180, v184
	v_mov_b32_e32 v181, 0
	v_lshlrev_b64 v[180:181], 12, v[180:181]
	v_lshl_add_u64 v[180:181], s[26:27], 0, v[180:181]
	v_lshl_add_u64 v[180:181], v[180:181], 0, v[72:73]
	v_or_b32_e32 v184, 48, v66
	v_cmp_gt_i32_e32 vcc, s93, v184
	v_add_u32_e32 v176, 0xffffc030, v66
	v_mov_b32_e32 v177, 0
	v_cndmask_b32_e32 v176, v176, v184, vcc
	v_cndmask_b32_e32 v187, v64, v78, vcc
	v_cndmask_b32_e32 v186, v79, v80, vcc
	v_lshlrev_b64 v[176:177], 12, v[176:177]
	v_lshl_add_u64 v[176:177], v[186:187], 0, v[176:177]
	v_lshl_add_u64 v[176:177], v[176:177], 0, v[72:73]
	v_mov_b32_e32 v182, v184
	v_mov_b32_e32 v183, 0
	v_lshlrev_b64 v[182:183], 12, v[182:183]
	v_lshl_add_u64 v[182:183], s[26:27], 0, v[182:183]
	v_lshl_add_u64 v[182:183], v[182:183], 0, v[72:73]
	global_load_dwordx4 v[82:85], v[74:75], off nt
	global_load_dwordx4 v[86:89], v[74:75], off offset:64 nt
	global_load_dwordx4 v[90:93], v[74:75], off offset:128 nt
	global_load_dwordx4 v[94:97], v[74:75], off offset:192 nt
	global_load_dwordx4 v[122:125], v[170:171], off nt
	global_load_dwordx4 v[126:129], v[170:171], off offset:64 nt
	global_load_dwordx4 v[130:133], v[170:171], off offset:128 nt
	global_load_dwordx4 v[134:137], v[170:171], off offset:192 nt
	global_load_dwordx4 v[138:141], v[172:173], off nt
	global_load_dwordx4 v[142:145], v[172:173], off offset:64 nt
	global_load_dwordx4 v[146:149], v[172:173], off offset:128 nt
	global_load_dwordx4 v[150:153], v[172:173], off offset:192 nt
	global_load_dwordx4 v[154:157], v[176:177], off nt
	global_load_dwordx4 v[158:161], v[176:177], off offset:64 nt
	global_load_dwordx4 v[162:165], v[176:177], off offset:128 nt
	global_load_dwordx4 v[166:169], v[176:177], off offset:192 nt
	s_waitcnt vmcnt(15)
	v_pk_add_f32 v[60:61], v[60:61], v[82:83]
	v_pk_add_f32 v[62:63], v[62:63], v[84:85]
	s_waitcnt vmcnt(14)
	v_pk_add_f32 v[56:57], v[56:57], v[86:87]
	v_pk_add_f32 v[58:59], v[58:59], v[88:89]
	s_waitcnt vmcnt(13)
	v_pk_add_f32 v[52:53], v[52:53], v[90:91]
	v_pk_add_f32 v[54:55], v[54:55], v[92:93]
	s_waitcnt vmcnt(12)
	v_pk_add_f32 v[48:49], v[48:49], v[94:95]
	v_pk_add_f32 v[50:51], v[50:51], v[96:97]
	global_store_dwordx4 v[76:77], v[60:63], off
	global_store_dwordx4 v[76:77], v[56:59], off offset:64
	global_store_dwordx4 v[76:77], v[52:55], off offset:128
	global_store_dwordx4 v[76:77], v[48:51], off offset:192
	s_waitcnt vmcnt(11)
	v_pk_add_f32 v[44:45], v[44:45], v[122:123]
	v_pk_add_f32 v[46:47], v[46:47], v[124:125]
	s_waitcnt vmcnt(10)
	v_pk_add_f32 v[40:41], v[40:41], v[126:127]
	v_pk_add_f32 v[42:43], v[42:43], v[128:129]
	s_waitcnt vmcnt(9)
	v_pk_add_f32 v[36:37], v[36:37], v[130:131]
	v_pk_add_f32 v[38:39], v[38:39], v[132:133]
	s_waitcnt vmcnt(8)
	v_pk_add_f32 v[32:33], v[32:33], v[134:135]
	v_pk_add_f32 v[34:35], v[34:35], v[136:137]
	global_store_dwordx4 v[178:179], v[44:47], off
	global_store_dwordx4 v[178:179], v[40:43], off offset:64
	global_store_dwordx4 v[178:179], v[36:39], off offset:128
	global_store_dwordx4 v[178:179], v[32:35], off offset:192
	s_waitcnt vmcnt(7)
	v_pk_add_f32 v[28:29], v[28:29], v[138:139]
	v_pk_add_f32 v[30:31], v[30:31], v[140:141]
	s_waitcnt vmcnt(6)
	v_pk_add_f32 v[24:25], v[24:25], v[142:143]
	v_pk_add_f32 v[26:27], v[26:27], v[144:145]
	s_waitcnt vmcnt(5)
	v_pk_add_f32 v[20:21], v[20:21], v[146:147]
	v_pk_add_f32 v[22:23], v[22:23], v[148:149]
	s_waitcnt vmcnt(4)
	v_pk_add_f32 v[16:17], v[16:17], v[150:151]
	v_pk_add_f32 v[18:19], v[18:19], v[152:153]
	global_store_dwordx4 v[180:181], v[28:31], off
	global_store_dwordx4 v[180:181], v[24:27], off offset:64
	global_store_dwordx4 v[180:181], v[20:23], off offset:128
	global_store_dwordx4 v[180:181], v[16:19], off offset:192
	s_waitcnt vmcnt(3)
	v_pk_add_f32 v[12:13], v[12:13], v[154:155]
	v_pk_add_f32 v[14:15], v[14:15], v[156:157]
	s_waitcnt vmcnt(2)
	v_pk_add_f32 v[8:9], v[8:9], v[158:159]
	v_pk_add_f32 v[10:11], v[10:11], v[160:161]
	s_waitcnt vmcnt(1)
	v_pk_add_f32 v[4:5], v[4:5], v[162:163]
	v_pk_add_f32 v[6:7], v[6:7], v[164:165]
	s_waitcnt vmcnt(0)
	v_pk_add_f32 v[0:1], v[0:1], v[166:167]
	v_pk_add_f32 v[2:3], v[2:3], v[168:169]
	global_store_dwordx4 v[182:183], v[12:15], off
	global_store_dwordx4 v[182:183], v[8:11], off offset:64
	global_store_dwordx4 v[182:183], v[4:7], off offset:128
	global_store_dwordx4 v[182:183], v[0:3], off offset:192
	s_cbranch_scc1 .LBB0_754

.LBB0_950:
	v_lshl_add_u32 v66, s92, 7, v99
	v_ashrrev_i32_e32 v67, 31, v66
	v_readlane_b32 s12, v254, 3
	v_lshlrev_b64 v[68:69], 12, v[66:67]
	v_readlane_b32 s26, v254, 17
	v_readlane_b32 s27, v254, 18
	s_waitcnt vmcnt(0)
	s_barrier
	v_lshl_add_u64 v[70:71], s[26:27], 0, v[68:69]
	v_lshl_or_b32 v68, s91, 7, v98
	v_ashrrev_i32_e32 v69, 31, v68
	v_lshlrev_b64 v[68:69], 2, v[68:69]
	v_lshl_add_u64 v[74:75], v[70:71], 0, v[68:69]
	v_or_b32_e32 v170, 16, v66
	v_ashrrev_i32_e32 v171, 31, v170
	v_lshlrev_b64 v[170:171], 12, v[170:171]
	v_lshl_add_u64 v[170:171], s[26:27], 0, v[170:171]
	v_lshl_add_u64 v[170:171], v[170:171], 0, v[68:69]
	v_or_b32_e32 v172, 32, v66
	v_ashrrev_i32_e32 v173, 31, v172
	v_lshlrev_b64 v[172:173], 12, v[172:173]
	v_lshl_add_u64 v[172:173], s[26:27], 0, v[172:173]
	v_lshl_add_u64 v[172:173], v[172:173], 0, v[68:69]
	v_or_b32_e32 v176, 48, v66
	v_ashrrev_i32_e32 v177, 31, v176
	v_lshlrev_b64 v[176:177], 12, v[176:177]
	v_lshl_add_u64 v[176:177], s[26:27], 0, v[176:177]
	v_lshl_add_u64 v[176:177], v[176:177], 0, v[68:69]
	global_load_dwordx4 v[82:85], v[74:75], off
	global_load_dwordx4 v[86:89], v[74:75], off offset:64
	global_load_dwordx4 v[90:93], v[74:75], off offset:128
	global_load_dwordx4 v[94:97], v[74:75], off offset:192
	global_load_dwordx4 v[122:125], v[170:171], off
	global_load_dwordx4 v[126:129], v[170:171], off offset:64
	global_load_dwordx4 v[130:133], v[170:171], off offset:128
	global_load_dwordx4 v[134:137], v[170:171], off offset:192
	global_load_dwordx4 v[138:141], v[172:173], off
	global_load_dwordx4 v[142:145], v[172:173], off offset:64
	global_load_dwordx4 v[146:149], v[172:173], off offset:128
	global_load_dwordx4 v[150:153], v[172:173], off offset:192
	global_load_dwordx4 v[154:157], v[176:177], off
	global_load_dwordx4 v[158:161], v[176:177], off offset:64
	global_load_dwordx4 v[162:165], v[176:177], off offset:128
	global_load_dwordx4 v[166:169], v[176:177], off offset:192
	s_add_i32 s3, s3, s85
	s_add_i32 s90, s90, s28
	s_cmpk_gt_i32 s3, 0x87
	v_readlane_b32 s13, v254, 4
	v_readlane_b32 s14, v254, 5
	v_readlane_b32 s15, v254, 6
	v_readlane_b32 s16, v254, 7
	v_readlane_b32 s17, v254, 8
	v_readlane_b32 s18, v254, 9
	v_readlane_b32 s19, v254, 10
	v_readlane_b32 s20, v254, 11
	v_readlane_b32 s21, v254, 12
	v_readlane_b32 s22, v254, 13
	v_readlane_b32 s23, v254, 14
	v_readlane_b32 s24, v254, 15
	v_readlane_b32 s25, v254, 16
	s_waitcnt vmcnt(15)
	v_pk_add_f32 v[60:61], v[60:61], v[82:83]
	v_pk_add_f32 v[62:63], v[62:63], v[84:85]
	s_waitcnt vmcnt(14)
	v_pk_add_f32 v[56:57], v[56:57], v[86:87]
	v_pk_add_f32 v[58:59], v[58:59], v[88:89]
	s_waitcnt vmcnt(13)
	v_pk_add_f32 v[52:53], v[52:53], v[90:91]
	v_pk_add_f32 v[54:55], v[54:55], v[92:93]
	s_waitcnt vmcnt(12)
	v_pk_add_f32 v[48:49], v[48:49], v[94:95]
	v_pk_add_f32 v[50:51], v[50:51], v[96:97]
	global_store_dwordx4 v[74:75], v[60:63], off
	global_store_dwordx4 v[74:75], v[56:59], off offset:64
	global_store_dwordx4 v[74:75], v[52:55], off offset:128
	global_store_dwordx4 v[74:75], v[48:51], off offset:192
	s_waitcnt vmcnt(11)
	v_pk_add_f32 v[44:45], v[44:45], v[122:123]
	v_pk_add_f32 v[46:47], v[46:47], v[124:125]
	s_waitcnt vmcnt(10)
	v_pk_add_f32 v[40:41], v[40:41], v[126:127]
	v_pk_add_f32 v[42:43], v[42:43], v[128:129]
	s_waitcnt vmcnt(9)
	v_pk_add_f32 v[36:37], v[36:37], v[130:131]
	v_pk_add_f32 v[38:39], v[38:39], v[132:133]
	s_waitcnt vmcnt(8)
	v_pk_add_f32 v[32:33], v[32:33], v[134:135]
	v_pk_add_f32 v[34:35], v[34:35], v[136:137]
	global_store_dwordx4 v[170:171], v[44:47], off
	global_store_dwordx4 v[170:171], v[40:43], off offset:64
	global_store_dwordx4 v[170:171], v[36:39], off offset:128
	global_store_dwordx4 v[170:171], v[32:35], off offset:192
	s_waitcnt vmcnt(7)
	v_pk_add_f32 v[28:29], v[28:29], v[138:139]
	v_pk_add_f32 v[30:31], v[30:31], v[140:141]
	s_waitcnt vmcnt(6)
	v_pk_add_f32 v[24:25], v[24:25], v[142:143]
	v_pk_add_f32 v[26:27], v[26:27], v[144:145]
	s_waitcnt vmcnt(5)
	v_pk_add_f32 v[20:21], v[20:21], v[146:147]
	v_pk_add_f32 v[22:23], v[22:23], v[148:149]
	s_waitcnt vmcnt(4)
	v_pk_add_f32 v[16:17], v[16:17], v[150:151]
	v_pk_add_f32 v[18:19], v[18:19], v[152:153]
	global_store_dwordx4 v[172:173], v[28:31], off
	global_store_dwordx4 v[172:173], v[24:27], off offset:64
	global_store_dwordx4 v[172:173], v[20:23], off offset:128
	global_store_dwordx4 v[172:173], v[16:19], off offset:192
	s_waitcnt vmcnt(3)
	v_pk_add_f32 v[12:13], v[12:13], v[154:155]
	v_pk_add_f32 v[14:15], v[14:15], v[156:157]
	s_waitcnt vmcnt(2)
	v_pk_add_f32 v[8:9], v[8:9], v[158:159]
	v_pk_add_f32 v[10:11], v[10:11], v[160:161]
	s_waitcnt vmcnt(1)
	v_pk_add_f32 v[4:5], v[4:5], v[162:163]
	v_pk_add_f32 v[6:7], v[6:7], v[164:165]
	s_waitcnt vmcnt(0)
	v_pk_add_f32 v[0:1], v[0:1], v[166:167]
	v_pk_add_f32 v[2:3], v[2:3], v[168:169]
	global_store_dwordx4 v[176:177], v[12:15], off
	global_store_dwordx4 v[176:177], v[8:11], off offset:64
	global_store_dwordx4 v[176:177], v[4:7], off offset:128
	global_store_dwordx4 v[176:177], v[0:3], off offset:192
	s_cbranch_scc1 .LBB0_955
